# v095 + P1 K-loop load segments: stage loads issued after the first and second group of 4 fragment reads (early LDS-DMA issue without a contiguous 16-read burst)
# baseline (speedup 1.0000x reference)
; #define PG8_STAGE(bufoff, gbase, voff) do { _Pragma("unroll") for (int _i = 0; _i < 2; ++_i) \
;         __builtin_amdgcn_global_load_lds((const unsigned*)((const char*)(gbase) + (voff)[_i]), (PG8_LAS unsigned*)(lds + (bufoff) + ldsw + _i * 8192), 16, 0, 0); } while (0)
; #define PG8_LDA(dst, b, h) do { _Pragma("unroll") for (int m = 0; m < 4; ++m) _Pragma("unroll") for (int k = 0; k < 2; ++k) dst[m][k] = *(const PG8_LAS bf16x8*)(lds + PG8_SA(b, h) + aoff + m * 2048 + k * 1024); } while (0)
; #define PG8_LDB(dst, b, h) do { _Pragma("unroll") for (int n = 0; n < 2; ++n) _Pragma("unroll") for (int k = 0; k < 2; ++k) dst[n][k] = *(const PG8_LAS bf16x8*)(lds + PG8_SB(b, h) + boff + n * 2048 + k * 1024); } while (0)
; #define PG8_MMA(ai, bj, At, Bt) do { __builtin_amdgcn_s_setprio(1); _Pragma("unroll") for (int m = 0; m < 4; ++m) _Pragma("unroll") for (int n = 0; n < 2; ++n) _Pragma("unroll") for (int k = 0; k < 2; ++k) \
;         acc[ai][bj][m][n] = __builtin_amdgcn_mfma_f32_16x16x32_bf16(Bt[n][k], At[m][k], acc[ai][bj][m][n], 0, 0, 0); __builtin_amdgcn_s_setprio(0); } while (0)
; #define PG8_WAIT_V(n) asm volatile("s_waitcnt vmcnt(" #n ")" ::: "memory")
; #define PG8_WAIT_L(n) asm volatile("s_waitcnt lgkmcnt(" #n ")" ::: "memory")
; #define PG8_BAR __builtin_amdgcn_s_barrier()
; #define PG8_SCHED __builtin_amdgcn_sched_barrier(0)
; template <class Epi, class Sched, bool ALIGN_EPI = false, bool SP2 = false, bool RS = false, bool BPRE = false>
; __device__ __forceinline__ void gemm_phase(PG8_LAS unsigned char* lds, const Gemm g, const Sched& S, const Epi& E, const float* rs_ss = nullptr, PG8_LAS float* rs_tab = nullptr) {
;     ...
;         const char* nA = has_next ? (const char*)g.A + (size_t)nxt.pm * tstep : cA; const char* nB = has_next ? (const char*)g.Bt + (size_t)nxt.pn * tstep : cB;
;     ...
;             PG8_LDB(B0, 0, 0); PG8_LDB(B1, 0, 1); PG8_SCHED; PG8_LDA(At, 0, 0); PG8_STAGE(PG8_SA(1, 1), a1 + hstep, voffA);
;             PG8_WAIT_V(8); PG8_WAIT_L(0); PG8_BAR; PG8_MMA(0, 0, At, B0); PG8_MMA(0, 1, At, B1); PG8_BAR; PG8_SCHED;
;             PG8_LDA(At, 0, 1); PG8_STAGE(PG8_SB(0, 0), b2, voffB); PG8_STAGE(PG8_SB(0, 1), b2 + hstep, voffB); PG8_STAGE(PG8_SA(0, 0), a2, voffA);
;             PG8_WAIT_V(8); PG8_WAIT_L(0); PG8_BAR; PG8_MMA(1, 0, At, B0); PG8_MMA(1, 1, At, B1); PG8_BAR; PG8_SCHED;
.LBB0_195:
	s_ashr_i32 s19, s18, 31
	s_lshl_b64 s[20:21], s[18:19], 20
	s_add_u32 s20, s30, s20
	s_addc_u32 s21, s31, s21
	s_and_b64 s[44:45], s[6:7], exec
	s_cselect_b32 s5, s21, s57
	s_cselect_b32 s19, s20, s56
	s_ashr_i32 s17, s16, 31
	s_lshl_b64 s[44:45], s[16:17], 20
	s_add_u32 s44, s24, s44
	s_addc_u32 s45, s25, s45
	s_and_b64 s[60:61], s[6:7], exec
	s_cselect_b32 s17, s45, s59
	s_cselect_b32 s47, s44, s58
	s_add_u32 s56, s56, 0x84000
	s_addc_u32 s57, s57, 0
	s_add_u32 s87, s58, 0x8000
	s_addc_u32 s88, s59, 0
	s_mov_b32 s89, -2
	s_waitcnt lgkmcnt(0)
	ds_read_b128 v[130:133], v161
	ds_read_b128 v[134:137], v161 offset:1024
	ds_read_b128 v[152:155], v161 offset:2048
	ds_read_b128 v[156:159], v161 offset:3072
	s_add_u32 s58, s56, 0xfff84000
	s_addc_u32 s59, s57, -1
	s_cmp_eq_u32 s89, 28
	s_cselect_b32 s70, s19, s58
	s_cselect_b32 s71, s5, s59
	s_cselect_b32 s60, s47, s87
	s_cselect_b32 s61, s17, s88
	s_add_u32 s58, s70, 0x4000
	s_addc_u32 s59, s71, 0
	v_lshl_add_u64 v[178:179], s[56:57], 0, v[138:139]
	s_add_i32 m0, s72, 0xc000
	s_nop 0
	global_load_lds_dwordx4 v[178:179], off
	ds_read_b128 v[166:169], v162
	ds_read_b128 v[170:173], v162 offset:1024
	ds_read_b128 v[174:177], v162 offset:2048
	ds_read_b128 v[182:185], v162 offset:3072
	v_lshl_add_u64 v[178:179], s[56:57], 0, v[146:147]
	s_add_i32 m0, s72, 0xe000
	s_nop 0
	global_load_lds_dwordx4 v[178:179], off
	ds_read_b128 v[188:191], v163
	ds_read_b128 v[192:195], v163 offset:1024
	ds_read_b128 v[196:199], v163 offset:2048
	ds_read_b128 v[200:203], v163 offset:3072
	ds_read_b128 v[204:207], v163 offset:4096
	ds_read_b128 v[208:211], v163 offset:5120
	ds_read_b128 v[212:215], v163 offset:6144
	ds_read_b128 v[216:219], v163 offset:7168
	s_waitcnt vmcnt(8)
	s_waitcnt lgkmcnt(0)
	s_barrier
	s_setprio 1
	s_waitcnt lgkmcnt(0)
	v_mfma_f32_16x16x32_bf16 v[126:129], v[130:133], v[188:191], 0
	v_mfma_f32_16x16x32_bf16 v[126:129], v[134:137], v[192:195], v[126:129]
	v_mfma_f32_16x16x32_bf16 v[122:125], v[156:159], v[192:195], 0
	v_mfma_f32_16x16x32_bf16 v[122:125], v[152:155], v[188:191], v[122:125]
	v_mfma_f32_16x16x32_bf16 v[106:109], v[152:155], v[196:199], 0
	v_mfma_f32_16x16x32_bf16 v[106:109], v[156:159], v[200:203], v[106:109]
	v_mfma_f32_16x16x32_bf16 v[110:113], v[134:137], v[200:203], 0
	v_mfma_f32_16x16x32_bf16 v[110:113], v[130:133], v[196:199], v[110:113]
	v_mfma_f32_16x16x32_bf16 v[94:97], v[130:133], v[204:207], 0
	v_mfma_f32_16x16x32_bf16 v[94:97], v[134:137], v[208:211], v[94:97]
	v_mfma_f32_16x16x32_bf16 v[90:93], v[156:159], v[208:211], 0
	v_mfma_f32_16x16x32_bf16 v[90:93], v[152:155], v[204:207], v[90:93]
	v_mfma_f32_16x16x32_bf16 v[74:77], v[152:155], v[212:215], 0
	v_mfma_f32_16x16x32_bf16 v[74:77], v[156:159], v[216:219], v[74:77]
	v_mfma_f32_16x16x32_bf16 v[78:81], v[134:137], v[216:219], 0
	v_mfma_f32_16x16x32_bf16 v[78:81], v[130:133], v[212:215], v[78:81]
	s_setprio 0
	s_setprio 1
	v_mfma_f32_16x16x32_bf16 v[70:73], v[166:169], v[212:215], 0
	v_mfma_f32_16x16x32_bf16 v[70:73], v[170:173], v[216:219], v[70:73]
	v_mfma_f32_16x16x32_bf16 v[66:69], v[182:185], v[216:219], 0
	v_mfma_f32_16x16x32_bf16 v[66:69], v[174:177], v[212:215], v[66:69]
	v_mfma_f32_16x16x32_bf16 v[82:85], v[174:177], v[204:207], 0
	v_mfma_f32_16x16x32_bf16 v[82:85], v[182:185], v[208:211], v[82:85]
	v_mfma_f32_16x16x32_bf16 v[86:89], v[170:173], v[208:211], 0
	v_mfma_f32_16x16x32_bf16 v[86:89], v[166:169], v[204:207], v[86:89]
	v_mfma_f32_16x16x32_bf16 v[102:105], v[166:169], v[196:199], 0
	v_mfma_f32_16x16x32_bf16 v[102:105], v[170:173], v[200:203], v[102:105]
	v_mfma_f32_16x16x32_bf16 v[98:101], v[182:185], v[200:203], 0
	v_mfma_f32_16x16x32_bf16 v[98:101], v[174:177], v[196:199], v[98:101]
	v_mfma_f32_16x16x32_bf16 v[114:117], v[174:177], v[188:191], 0
	v_mfma_f32_16x16x32_bf16 v[114:117], v[182:185], v[192:195], v[114:117]
	v_mfma_f32_16x16x32_bf16 v[118:121], v[170:173], v[192:195], 0
	v_mfma_f32_16x16x32_bf16 v[118:121], v[166:169], v[188:191], v[118:121]
	s_setprio 0
	s_barrier
	ds_read_b128 v[188:191], v163 offset:16384
	ds_read_b128 v[192:195], v163 offset:17408
	ds_read_b128 v[196:199], v163 offset:18432
	ds_read_b128 v[200:203], v163 offset:19456
	s_add_i32 s90, s83, s15
	v_lshl_add_u64 v[178:179], s[60:61], 0, v[138:139]
	s_mov_b32 m0, s90
	s_nop 0
	global_load_lds_dwordx4 v[178:179], off
	ds_read_b128 v[204:207], v163 offset:20480
	ds_read_b128 v[208:211], v163 offset:21504
	ds_read_b128 v[212:215], v163 offset:22528
	ds_read_b128 v[216:219], v163 offset:23552
	s_add_i32 m0, s90, 0x2000
	s_add_u32 s90, s60, 0x80000
	v_lshl_add_u64 v[178:179], s[60:61], 0, v[140:141]
	s_addc_u32 s91, s61, 0
	s_add_i32 s92, s86, s15
	global_load_lds_dwordx4 v[178:179], off
	v_lshl_add_u64 v[178:179], s[90:91], 0, v[138:139]
	s_mov_b32 m0, s92
	s_nop 0
	global_load_lds_dwordx4 v[178:179], off
	v_lshl_add_u64 v[178:179], s[90:91], 0, v[140:141]
	s_add_i32 m0, s92, 0x2000
	s_nop 0
	global_load_lds_dwordx4 v[178:179], off
	v_lshl_add_u64 v[178:179], s[70:71], 0, v[138:139]
	s_mov_b32 m0, s72
	s_nop 0
	global_load_lds_dwordx4 v[178:179], off
	v_lshl_add_u64 v[178:179], s[70:71], 0, v[140:141]
	s_mov_b32 m0, s73
	s_nop 0
	global_load_lds_dwordx4 v[178:179], off
	s_waitcnt vmcnt(8)
	s_waitcnt lgkmcnt(0)
	s_barrier
; #define PG8_STAGE(bufoff, gbase, voff) do { _Pragma("unroll") for (int _i = 0; _i < 2; ++_i) \
;         __builtin_amdgcn_global_load_lds((const unsigned*)((const char*)(gbase) + (voff)[_i]), (PG8_LAS unsigned*)(lds + (bufoff) + ldsw + _i * 8192), 16, 0, 0); } while (0)
; #define PG8_LDA(dst, b, h) do { _Pragma("unroll") for (int m = 0; m < 4; ++m) _Pragma("unroll") for (int k = 0; k < 2; ++k) dst[m][k] = *(const PG8_LAS bf16x8*)(lds + PG8_SA(b, h) + aoff + m * 2048 + k * 1024); } while (0)
; #define PG8_LDB(dst, b, h) do { _Pragma("unroll") for (int n = 0; n < 2; ++n) _Pragma("unroll") for (int k = 0; k < 2; ++k) dst[n][k] = *(const PG8_LAS bf16x8*)(lds + PG8_SB(b, h) + boff + n * 2048 + k * 1024); } while (0)
; #define PG8_MMA(ai, bj, At, Bt) do { __builtin_amdgcn_s_setprio(1); _Pragma("unroll") for (int m = 0; m < 4; ++m) _Pragma("unroll") for (int n = 0; n < 2; ++n) _Pragma("unroll") for (int k = 0; k < 2; ++k) \
;         acc[ai][bj][m][n] = __builtin_amdgcn_mfma_f32_16x16x32_bf16(Bt[n][k], At[m][k], acc[ai][bj][m][n], 0, 0, 0); __builtin_amdgcn_s_setprio(0); } while (0)
; #define PG8_WAIT_V(n) asm volatile("s_waitcnt vmcnt(" #n ")" ::: "memory")
; #define PG8_WAIT_L(n) asm volatile("s_waitcnt lgkmcnt(" #n ")" ::: "memory")
; #define PG8_BAR __builtin_amdgcn_s_barrier()
; #define PG8_SCHED __builtin_amdgcn_sched_barrier(0)
; template <class Epi, class Sched, bool ALIGN_EPI = false, bool SP2 = false, bool RS = false, bool BPRE = false>
; __device__ __forceinline__ void gemm_phase(PG8_LAS unsigned char* lds, const Gemm g, const Sched& S, const Epi& E, const float* rs_ss = nullptr, PG8_LAS float* rs_tab = nullptr) {
;     ...
;             PG8_WAIT_V(8); PG8_WAIT_L(0); PG8_BAR; PG8_MMA(1, 0, At, B0); PG8_MMA(1, 1, At, B1); PG8_BAR; PG8_SCHED;
;             PG8_LDB(B0, 1, 0); PG8_LDB(B1, 1, 1); PG8_SCHED; PG8_LDA(At, 1, 0); PG8_STAGE(PG8_SA(0, 1), a2 + hstep, voffA);
;             PG8_WAIT_V(8); PG8_WAIT_L(0); PG8_BAR; PG8_MMA(0, 0, At, B0); PG8_MMA(0, 1, At, B1); PG8_BAR; PG8_SCHED;
	s_setprio 1
	s_waitcnt lgkmcnt(0)
	v_mfma_f32_16x16x32_bf16 v[62:65], v[130:133], v[188:191], 0
	v_mfma_f32_16x16x32_bf16 v[62:65], v[134:137], v[192:195], v[62:65]
	v_mfma_f32_16x16x32_bf16 v[58:61], v[156:159], v[192:195], 0
	v_mfma_f32_16x16x32_bf16 v[58:61], v[152:155], v[188:191], v[58:61]
	v_mfma_f32_16x16x32_bf16 v[42:45], v[152:155], v[196:199], 0
	v_mfma_f32_16x16x32_bf16 v[42:45], v[156:159], v[200:203], v[42:45]
	v_mfma_f32_16x16x32_bf16 v[46:49], v[134:137], v[200:203], 0
	v_mfma_f32_16x16x32_bf16 v[46:49], v[130:133], v[196:199], v[46:49]
	v_mfma_f32_16x16x32_bf16 v[30:33], v[130:133], v[204:207], 0
	v_mfma_f32_16x16x32_bf16 v[30:33], v[134:137], v[208:211], v[30:33]
	v_mfma_f32_16x16x32_bf16 v[26:29], v[156:159], v[208:211], 0
	v_mfma_f32_16x16x32_bf16 v[26:29], v[152:155], v[204:207], v[26:29]
	v_mfma_f32_16x16x32_bf16 v[10:13], v[152:155], v[212:215], 0
	v_mfma_f32_16x16x32_bf16 v[10:13], v[156:159], v[216:219], v[10:13]
	v_mfma_f32_16x16x32_bf16 v[14:17], v[134:137], v[216:219], 0
	v_mfma_f32_16x16x32_bf16 v[14:17], v[130:133], v[212:215], v[14:17]
	s_setprio 0
	s_setprio 1
	v_mfma_f32_16x16x32_bf16 v[6:9], v[166:169], v[212:215], 0
	v_mfma_f32_16x16x32_bf16 v[6:9], v[170:173], v[216:219], v[6:9]
	v_mfma_f32_16x16x32_bf16 v[2:5], v[182:185], v[216:219], 0
	v_mfma_f32_16x16x32_bf16 v[2:5], v[174:177], v[212:215], v[2:5]
	v_mfma_f32_16x16x32_bf16 v[18:21], v[174:177], v[204:207], 0
	v_mfma_f32_16x16x32_bf16 v[18:21], v[182:185], v[208:211], v[18:21]
	v_mfma_f32_16x16x32_bf16 v[22:25], v[170:173], v[208:211], 0
	v_mfma_f32_16x16x32_bf16 v[22:25], v[166:169], v[204:207], v[22:25]
	v_mfma_f32_16x16x32_bf16 v[38:41], v[166:169], v[196:199], 0
	v_mfma_f32_16x16x32_bf16 v[38:41], v[170:173], v[200:203], v[38:41]
	v_mfma_f32_16x16x32_bf16 v[34:37], v[182:185], v[200:203], 0
	v_mfma_f32_16x16x32_bf16 v[34:37], v[174:177], v[196:199], v[34:37]
	v_mfma_f32_16x16x32_bf16 v[50:53], v[174:177], v[188:191], 0
	v_mfma_f32_16x16x32_bf16 v[50:53], v[182:185], v[192:195], v[50:53]
	v_mfma_f32_16x16x32_bf16 v[54:57], v[170:173], v[192:195], 0
	v_mfma_f32_16x16x32_bf16 v[54:57], v[166:169], v[188:191], v[54:57]
	s_setprio 0
	s_barrier
	s_add_i32 s90, 0, 0x18000
	v_add_u32_e32 v143, s90, v160
	s_add_i32 s91, 0, 0x1c000
	ds_read_b128 v[130:133], v143
	ds_read_b128 v[134:137], v143 offset:1024
	ds_read_b128 v[152:155], v143 offset:2048
	ds_read_b128 v[156:159], v143 offset:3072
	s_add_u32 s70, s70, 0x80000
	s_addc_u32 s71, s71, 0
	s_mov_b32 m0, s74
	v_lshl_add_u64 v[178:179], s[70:71], 0, v[138:139]
	global_load_lds_dwordx4 v[178:179], off
	v_add_u32_e32 v143, s91, v160
	ds_read_b128 v[166:169], v143
	ds_read_b128 v[170:173], v143 offset:1024
	ds_read_b128 v[174:177], v143 offset:2048
	ds_read_b128 v[182:185], v143 offset:3072
	v_lshl_add_u64 v[178:179], s[70:71], 0, v[140:141]
	s_mov_b32 m0, s75
	s_nop 0
	global_load_lds_dwordx4 v[178:179], off
	ds_read_b128 v[188:191], v163 offset:32768
	ds_read_b128 v[192:195], v163 offset:33792
	ds_read_b128 v[196:199], v163 offset:34816
	ds_read_b128 v[200:203], v163 offset:35840
	ds_read_b128 v[204:207], v163 offset:36864
	ds_read_b128 v[208:211], v163 offset:37888
	ds_read_b128 v[212:215], v163 offset:38912
	ds_read_b128 v[216:219], v163 offset:39936
	s_waitcnt vmcnt(8)
	s_waitcnt lgkmcnt(0)
	s_barrier
	s_setprio 1
	s_waitcnt lgkmcnt(0)
	v_mfma_f32_16x16x32_bf16 v[126:129], v[130:133], v[188:191], v[126:129]
	v_mfma_f32_16x16x32_bf16 v[126:129], v[134:137], v[192:195], v[126:129]
	v_mfma_f32_16x16x32_bf16 v[122:125], v[156:159], v[192:195], v[122:125]
	v_mfma_f32_16x16x32_bf16 v[122:125], v[152:155], v[188:191], v[122:125]
	v_mfma_f32_16x16x32_bf16 v[106:109], v[152:155], v[196:199], v[106:109]
	v_mfma_f32_16x16x32_bf16 v[106:109], v[156:159], v[200:203], v[106:109]
	v_mfma_f32_16x16x32_bf16 v[110:113], v[134:137], v[200:203], v[110:113]
	v_mfma_f32_16x16x32_bf16 v[110:113], v[130:133], v[196:199], v[110:113]
	v_mfma_f32_16x16x32_bf16 v[94:97], v[130:133], v[204:207], v[94:97]
	v_mfma_f32_16x16x32_bf16 v[94:97], v[134:137], v[208:211], v[94:97]
	v_mfma_f32_16x16x32_bf16 v[90:93], v[156:159], v[208:211], v[90:93]
	v_mfma_f32_16x16x32_bf16 v[90:93], v[152:155], v[204:207], v[90:93]
	v_mfma_f32_16x16x32_bf16 v[74:77], v[152:155], v[212:215], v[74:77]
	v_mfma_f32_16x16x32_bf16 v[74:77], v[156:159], v[216:219], v[74:77]
	v_mfma_f32_16x16x32_bf16 v[78:81], v[134:137], v[216:219], v[78:81]
	v_mfma_f32_16x16x32_bf16 v[78:81], v[130:133], v[212:215], v[78:81]
	s_setprio 0
	s_setprio 1
	v_mfma_f32_16x16x32_bf16 v[70:73], v[166:169], v[212:215], v[70:73]
	v_mfma_f32_16x16x32_bf16 v[70:73], v[170:173], v[216:219], v[70:73]
	v_mfma_f32_16x16x32_bf16 v[66:69], v[182:185], v[216:219], v[66:69]
	v_mfma_f32_16x16x32_bf16 v[66:69], v[174:177], v[212:215], v[66:69]
	v_mfma_f32_16x16x32_bf16 v[82:85], v[174:177], v[204:207], v[82:85]
	v_mfma_f32_16x16x32_bf16 v[82:85], v[182:185], v[208:211], v[82:85]
	v_mfma_f32_16x16x32_bf16 v[86:89], v[170:173], v[208:211], v[86:89]
	v_mfma_f32_16x16x32_bf16 v[86:89], v[166:169], v[204:207], v[86:89]
	v_mfma_f32_16x16x32_bf16 v[102:105], v[166:169], v[196:199], v[102:105]
	v_mfma_f32_16x16x32_bf16 v[102:105], v[170:173], v[200:203], v[102:105]
	v_mfma_f32_16x16x32_bf16 v[98:101], v[182:185], v[200:203], v[98:101]
	v_mfma_f32_16x16x32_bf16 v[98:101], v[174:177], v[196:199], v[98:101]
	v_mfma_f32_16x16x32_bf16 v[114:117], v[174:177], v[188:191], v[114:117]
	v_mfma_f32_16x16x32_bf16 v[114:117], v[182:185], v[192:195], v[114:117]
	v_mfma_f32_16x16x32_bf16 v[118:121], v[170:173], v[192:195], v[118:121]
	v_mfma_f32_16x16x32_bf16 v[118:121], v[166:169], v[188:191], v[118:121]
	s_setprio 0
	s_barrier
; #define PG8_STAGE(bufoff, gbase, voff) do { _Pragma("unroll") for (int _i = 0; _i < 2; ++_i) \
;         __builtin_amdgcn_global_load_lds((const unsigned*)((const char*)(gbase) + (voff)[_i]), (PG8_LAS unsigned*)(lds + (bufoff) + ldsw + _i * 8192), 16, 0, 0); } while (0)
; #define PG8_LDA(dst, b, h) do { _Pragma("unroll") for (int m = 0; m < 4; ++m) _Pragma("unroll") for (int k = 0; k < 2; ++k) dst[m][k] = *(const PG8_LAS bf16x8*)(lds + PG8_SA(b, h) + aoff + m * 2048 + k * 1024); } while (0)
; #define PG8_LDB(dst, b, h) do { _Pragma("unroll") for (int n = 0; n < 2; ++n) _Pragma("unroll") for (int k = 0; k < 2; ++k) dst[n][k] = *(const PG8_LAS bf16x8*)(lds + PG8_SB(b, h) + boff + n * 2048 + k * 1024); } while (0)
; template <class Epi, class Sched, bool ALIGN_EPI = false, bool SP2 = false, bool RS = false, bool BPRE = false>
; __device__ __forceinline__ void gemm_phase(PG8_LAS unsigned char* lds, const Gemm g, const Sched& S, const Epi& E, const float* rs_ss = nullptr, PG8_LAS float* rs_tab = nullptr) {
;     ...
;             const char* a1 = cA + (size_t)(t + 1) * kstep;
;             const char* a2 = last ? nA : cA + (size_t)(t + 2) * kstep; const char* b2 = last ? nB : cB + (size_t)(t + 2) * kstep;
;             const char* a3 = a2 + kstep; const char* b3 = b2 + kstep;
;             if (last && has_next) S.a_ready(nxt);
;             if constexpr (SP2) {
;             PG8_LDB(B0, 0, 0); PG8_LDB(B1, 0, 1); PG8_SCHED; PG8_LDA(At, 0, 0); PG8_STAGE(PG8_SA(1, 1), a1 + hstep, voffA);
;             PG8_WAIT_V(8); PG8_WAIT_L(0); PG8_BAR; PG8_MMA(0, 0, At, B0); PG8_MMA(0, 1, At, B1); PG8_BAR; PG8_SCHED;
;             PG8_LDA(At, 0, 1); PG8_STAGE(PG8_SB(0, 0), b2, voffB); PG8_STAGE(PG8_SB(0, 1), b2 + hstep, voffB); PG8_STAGE(PG8_SA(0, 0), a2, voffA);
;             PG8_WAIT_V(8); PG8_WAIT_L(0); PG8_BAR; PG8_MMA(1, 0, At, B0); PG8_MMA(1, 1, At, B1); PG8_BAR; PG8_SCHED;
;             PG8_LDB(B0, 1, 0); PG8_LDB(B1, 1, 1); PG8_SCHED; PG8_LDA(At, 1, 0); PG8_STAGE(PG8_SA(0, 1), a2 + hstep, voffA);
;             PG8_WAIT_V(8); PG8_WAIT_L(0); PG8_BAR; PG8_MMA(0, 0, At, B0); PG8_MMA(0, 1, At, B1); PG8_BAR; PG8_SCHED;
;             PG8_LDA(At, 1, 1); PG8_STAGE(PG8_SB(1, 0), b3, voffB); PG8_STAGE(PG8_SB(1, 1), b3 + hstep, voffB); PG8_STAGE(PG8_SA(1, 0), a3, voffA);
;             PG8_WAIT_V(8); PG8_WAIT_L(0); PG8_BAR; PG8_MMA(1, 0, At, B0); PG8_MMA(1, 1, At, B1); PG8_BAR; PG8_SCHED;
	ds_read_b128 v[188:191], v163 offset:49152
	ds_read_b128 v[192:195], v163 offset:50176
	ds_read_b128 v[196:199], v163 offset:51200
	ds_read_b128 v[200:203], v163 offset:52224
	s_add_u32 s70, s60, 0x4000
	s_addc_u32 s71, s61, 0
	s_add_i32 s90, s90, s15
	v_lshl_add_u64 v[178:179], s[70:71], 0, v[138:139]
	s_mov_b32 m0, s90
	s_nop 0
	global_load_lds_dwordx4 v[178:179], off
	ds_read_b128 v[204:207], v163 offset:53248
	ds_read_b128 v[208:211], v163 offset:54272
	ds_read_b128 v[212:215], v163 offset:55296
	ds_read_b128 v[216:219], v163 offset:56320
	s_add_i32 m0, s90, 0x2000
	s_add_u32 s60, s60, 0x84000
	v_lshl_add_u64 v[178:179], s[70:71], 0, v[140:141]
	s_addc_u32 s61, s61, 0
	s_add_i32 s70, s91, s15
	global_load_lds_dwordx4 v[178:179], off
	v_lshl_add_u64 v[178:179], s[60:61], 0, v[138:139]
	s_mov_b32 m0, s70
	s_nop 0
	global_load_lds_dwordx4 v[178:179], off
	v_lshl_add_u64 v[178:179], s[60:61], 0, v[140:141]
	s_add_i32 m0, s70, 0x2000
	s_nop 0
	global_load_lds_dwordx4 v[178:179], off
	v_lshl_add_u64 v[178:179], s[58:59], 0, v[138:139]
	s_mov_b32 m0, s79
	s_nop 0
	global_load_lds_dwordx4 v[178:179], off
	v_lshl_add_u64 v[178:179], s[58:59], 0, v[140:141]
	s_mov_b32 m0, s80
	s_nop 0
	global_load_lds_dwordx4 v[178:179], off
	s_waitcnt vmcnt(8)
	s_waitcnt lgkmcnt(0)
	s_barrier
	s_setprio 1
	s_waitcnt lgkmcnt(0)
	v_mfma_f32_16x16x32_bf16 v[62:65], v[130:133], v[188:191], v[62:65]
	v_mfma_f32_16x16x32_bf16 v[62:65], v[134:137], v[192:195], v[62:65]
	v_mfma_f32_16x16x32_bf16 v[58:61], v[156:159], v[192:195], v[58:61]
	v_mfma_f32_16x16x32_bf16 v[58:61], v[152:155], v[188:191], v[58:61]
	v_mfma_f32_16x16x32_bf16 v[42:45], v[152:155], v[196:199], v[42:45]
	v_mfma_f32_16x16x32_bf16 v[42:45], v[156:159], v[200:203], v[42:45]
	v_mfma_f32_16x16x32_bf16 v[46:49], v[134:137], v[200:203], v[46:49]
	v_mfma_f32_16x16x32_bf16 v[46:49], v[130:133], v[196:199], v[46:49]
	v_mfma_f32_16x16x32_bf16 v[30:33], v[130:133], v[204:207], v[30:33]
	v_mfma_f32_16x16x32_bf16 v[30:33], v[134:137], v[208:211], v[30:33]
	v_mfma_f32_16x16x32_bf16 v[26:29], v[156:159], v[208:211], v[26:29]
	v_mfma_f32_16x16x32_bf16 v[26:29], v[152:155], v[204:207], v[26:29]
	v_mfma_f32_16x16x32_bf16 v[10:13], v[152:155], v[212:215], v[10:13]
	v_mfma_f32_16x16x32_bf16 v[10:13], v[156:159], v[216:219], v[10:13]
	v_mfma_f32_16x16x32_bf16 v[14:17], v[134:137], v[216:219], v[14:17]
	v_mfma_f32_16x16x32_bf16 v[14:17], v[130:133], v[212:215], v[14:17]
	s_setprio 0
	s_setprio 1
	v_mfma_f32_16x16x32_bf16 v[6:9], v[166:169], v[212:215], v[6:9]
	v_mfma_f32_16x16x32_bf16 v[6:9], v[170:173], v[216:219], v[6:9]
	v_mfma_f32_16x16x32_bf16 v[2:5], v[182:185], v[216:219], v[2:5]
	v_mfma_f32_16x16x32_bf16 v[2:5], v[174:177], v[212:215], v[2:5]
	v_mfma_f32_16x16x32_bf16 v[18:21], v[174:177], v[204:207], v[18:21]
	v_mfma_f32_16x16x32_bf16 v[18:21], v[182:185], v[208:211], v[18:21]
	v_mfma_f32_16x16x32_bf16 v[22:25], v[170:173], v[208:211], v[22:25]
	v_mfma_f32_16x16x32_bf16 v[22:25], v[166:169], v[204:207], v[22:25]
	v_mfma_f32_16x16x32_bf16 v[38:41], v[166:169], v[196:199], v[38:41]
	v_mfma_f32_16x16x32_bf16 v[38:41], v[170:173], v[200:203], v[38:41]
	v_mfma_f32_16x16x32_bf16 v[34:37], v[182:185], v[200:203], v[34:37]
	v_mfma_f32_16x16x32_bf16 v[34:37], v[174:177], v[196:199], v[34:37]
	v_mfma_f32_16x16x32_bf16 v[50:53], v[174:177], v[188:191], v[50:53]
	v_mfma_f32_16x16x32_bf16 v[50:53], v[182:185], v[192:195], v[50:53]
	v_mfma_f32_16x16x32_bf16 v[54:57], v[170:173], v[192:195], v[54:57]
	v_mfma_f32_16x16x32_bf16 v[54:57], v[166:169], v[188:191], v[54:57]
	s_setprio 0
	s_barrier
	s_add_i32 s89, s89, 2
	s_add_u32 s56, s56, 0x8000
	s_addc_u32 s57, s57, 0
	s_add_u32 s87, s87, 0x8000
	s_addc_u32 s88, s88, 0
.LBB0_196:
	ds_read_b128 v[130:133], v161
	ds_read_b128 v[134:137], v161 offset:1024
	ds_read_b128 v[152:155], v161 offset:2048
	ds_read_b128 v[156:159], v161 offset:3072
	s_add_u32 s58, s56, 0xfff84000
	s_addc_u32 s59, s57, -1
	s_cmp_eq_u32 s89, 28
	s_cselect_b32 s70, s19, s58
	s_cselect_b32 s71, s5, s59
	s_cselect_b32 s60, s47, s87
	s_cselect_b32 s61, s17, s88
	s_add_u32 s58, s70, 0x4000
	s_addc_u32 s59, s71, 0
	v_lshl_add_u64 v[178:179], s[56:57], 0, v[138:139]
	s_add_i32 m0, s72, 0xc000
	s_nop 0
	global_load_lds_dwordx4 v[178:179], off
	ds_read_b128 v[166:169], v162
	ds_read_b128 v[170:173], v162 offset:1024
	ds_read_b128 v[174:177], v162 offset:2048
	ds_read_b128 v[182:185], v162 offset:3072
	v_lshl_add_u64 v[178:179], s[56:57], 0, v[146:147]
	s_add_i32 m0, s72, 0xe000
	s_nop 0
	global_load_lds_dwordx4 v[178:179], off
	ds_read_b128 v[188:191], v163
	ds_read_b128 v[192:195], v163 offset:1024
	ds_read_b128 v[196:199], v163 offset:2048
	ds_read_b128 v[200:203], v163 offset:3072
	ds_read_b128 v[204:207], v163 offset:4096
	ds_read_b128 v[208:211], v163 offset:5120
	ds_read_b128 v[212:215], v163 offset:6144
	ds_read_b128 v[216:219], v163 offset:7168
	s_waitcnt vmcnt(8)
	s_waitcnt lgkmcnt(0)
	s_barrier
; #define PG8_STAGE(bufoff, gbase, voff) do { _Pragma("unroll") for (int _i = 0; _i < 2; ++_i) \
;         __builtin_amdgcn_global_load_lds((const unsigned*)((const char*)(gbase) + (voff)[_i]), (PG8_LAS unsigned*)(lds + (bufoff) + ldsw + _i * 8192), 16, 0, 0); } while (0)
; #define PG8_LDA(dst, b, h) do { _Pragma("unroll") for (int m = 0; m < 4; ++m) _Pragma("unroll") for (int k = 0; k < 2; ++k) dst[m][k] = *(const PG8_LAS bf16x8*)(lds + PG8_SA(b, h) + aoff + m * 2048 + k * 1024); } while (0)
; #define PG8_MMA(ai, bj, At, Bt) do { __builtin_amdgcn_s_setprio(1); _Pragma("unroll") for (int m = 0; m < 4; ++m) _Pragma("unroll") for (int n = 0; n < 2; ++n) _Pragma("unroll") for (int k = 0; k < 2; ++k) \
;         acc[ai][bj][m][n] = __builtin_amdgcn_mfma_f32_16x16x32_bf16(Bt[n][k], At[m][k], acc[ai][bj][m][n], 0, 0, 0); __builtin_amdgcn_s_setprio(0); } while (0)
; #define PG8_WAIT_V(n) asm volatile("s_waitcnt vmcnt(" #n ")" ::: "memory")
; #define PG8_WAIT_L(n) asm volatile("s_waitcnt lgkmcnt(" #n ")" ::: "memory")
; #define PG8_BAR __builtin_amdgcn_s_barrier()
; #define PG8_SCHED __builtin_amdgcn_sched_barrier(0)
; template <class Epi, class Sched, bool ALIGN_EPI = false, bool SP2 = false, bool RS = false, bool BPRE = false>
; __device__ __forceinline__ void gemm_phase(PG8_LAS unsigned char* lds, const Gemm g, const Sched& S, const Epi& E, const float* rs_ss = nullptr, PG8_LAS float* rs_tab = nullptr) {
;     ...
;             PG8_WAIT_V(8); PG8_WAIT_L(0); PG8_BAR; PG8_MMA(0, 0, At, B0); PG8_MMA(0, 1, At, B1); PG8_BAR; PG8_SCHED;
;             PG8_LDA(At, 0, 1); PG8_STAGE(PG8_SB(0, 0), b2, voffB); PG8_STAGE(PG8_SB(0, 1), b2 + hstep, voffB); PG8_STAGE(PG8_SA(0, 0), a2, voffA);
;             PG8_WAIT_V(8); PG8_WAIT_L(0); PG8_BAR; PG8_MMA(1, 0, At, B0); PG8_MMA(1, 1, At, B1); PG8_BAR; PG8_SCHED;
	s_setprio 1
	s_waitcnt lgkmcnt(0)
	v_mfma_f32_16x16x32_bf16 v[126:129], v[130:133], v[188:191], v[126:129]
	v_mfma_f32_16x16x32_bf16 v[126:129], v[134:137], v[192:195], v[126:129]
	v_mfma_f32_16x16x32_bf16 v[122:125], v[156:159], v[192:195], v[122:125]
	v_mfma_f32_16x16x32_bf16 v[122:125], v[152:155], v[188:191], v[122:125]
	v_mfma_f32_16x16x32_bf16 v[106:109], v[152:155], v[196:199], v[106:109]
	v_mfma_f32_16x16x32_bf16 v[106:109], v[156:159], v[200:203], v[106:109]
	v_mfma_f32_16x16x32_bf16 v[110:113], v[134:137], v[200:203], v[110:113]
	v_mfma_f32_16x16x32_bf16 v[110:113], v[130:133], v[196:199], v[110:113]
	v_mfma_f32_16x16x32_bf16 v[94:97], v[130:133], v[204:207], v[94:97]
	v_mfma_f32_16x16x32_bf16 v[94:97], v[134:137], v[208:211], v[94:97]
	v_mfma_f32_16x16x32_bf16 v[90:93], v[156:159], v[208:211], v[90:93]
	v_mfma_f32_16x16x32_bf16 v[90:93], v[152:155], v[204:207], v[90:93]
	v_mfma_f32_16x16x32_bf16 v[74:77], v[152:155], v[212:215], v[74:77]
	v_mfma_f32_16x16x32_bf16 v[74:77], v[156:159], v[216:219], v[74:77]
	v_mfma_f32_16x16x32_bf16 v[78:81], v[134:137], v[216:219], v[78:81]
	v_mfma_f32_16x16x32_bf16 v[78:81], v[130:133], v[212:215], v[78:81]
	s_setprio 0
	s_setprio 1
	v_mfma_f32_16x16x32_bf16 v[70:73], v[166:169], v[212:215], v[70:73]
	v_mfma_f32_16x16x32_bf16 v[70:73], v[170:173], v[216:219], v[70:73]
	v_mfma_f32_16x16x32_bf16 v[66:69], v[182:185], v[216:219], v[66:69]
	v_mfma_f32_16x16x32_bf16 v[66:69], v[174:177], v[212:215], v[66:69]
	v_mfma_f32_16x16x32_bf16 v[82:85], v[174:177], v[204:207], v[82:85]
	v_mfma_f32_16x16x32_bf16 v[82:85], v[182:185], v[208:211], v[82:85]
	v_mfma_f32_16x16x32_bf16 v[86:89], v[170:173], v[208:211], v[86:89]
	v_mfma_f32_16x16x32_bf16 v[86:89], v[166:169], v[204:207], v[86:89]
	v_mfma_f32_16x16x32_bf16 v[102:105], v[166:169], v[196:199], v[102:105]
	v_mfma_f32_16x16x32_bf16 v[102:105], v[170:173], v[200:203], v[102:105]
	v_mfma_f32_16x16x32_bf16 v[98:101], v[182:185], v[200:203], v[98:101]
	v_mfma_f32_16x16x32_bf16 v[98:101], v[174:177], v[196:199], v[98:101]
	v_mfma_f32_16x16x32_bf16 v[114:117], v[174:177], v[188:191], v[114:117]
	v_mfma_f32_16x16x32_bf16 v[114:117], v[182:185], v[192:195], v[114:117]
	v_mfma_f32_16x16x32_bf16 v[118:121], v[170:173], v[192:195], v[118:121]
	v_mfma_f32_16x16x32_bf16 v[118:121], v[166:169], v[188:191], v[118:121]
	s_setprio 0
	s_barrier
	ds_read_b128 v[188:191], v163 offset:16384
	ds_read_b128 v[192:195], v163 offset:17408
	ds_read_b128 v[196:199], v163 offset:18432
	ds_read_b128 v[200:203], v163 offset:19456
	s_add_i32 s90, s83, s15
	v_lshl_add_u64 v[178:179], s[60:61], 0, v[138:139]
	s_mov_b32 m0, s90
	s_nop 0
	global_load_lds_dwordx4 v[178:179], off
	ds_read_b128 v[204:207], v163 offset:20480
	ds_read_b128 v[208:211], v163 offset:21504
	ds_read_b128 v[212:215], v163 offset:22528
	ds_read_b128 v[216:219], v163 offset:23552
	s_add_i32 m0, s90, 0x2000
	s_add_u32 s90, s60, 0x80000
	v_lshl_add_u64 v[178:179], s[60:61], 0, v[140:141]
	s_addc_u32 s91, s61, 0
	s_add_i32 s92, s86, s15
	global_load_lds_dwordx4 v[178:179], off
	v_lshl_add_u64 v[178:179], s[90:91], 0, v[138:139]
	s_mov_b32 m0, s92
	s_nop 0
	global_load_lds_dwordx4 v[178:179], off
	v_lshl_add_u64 v[178:179], s[90:91], 0, v[140:141]
	s_add_i32 m0, s92, 0x2000
	s_nop 0
	global_load_lds_dwordx4 v[178:179], off
	v_lshl_add_u64 v[178:179], s[70:71], 0, v[138:139]
	s_mov_b32 m0, s72
	s_nop 0
	global_load_lds_dwordx4 v[178:179], off
	v_lshl_add_u64 v[178:179], s[70:71], 0, v[140:141]
	s_mov_b32 m0, s73
	s_nop 0
	global_load_lds_dwordx4 v[178:179], off
	s_waitcnt vmcnt(8)
	s_waitcnt lgkmcnt(0)
	s_barrier
	s_setprio 1
	s_waitcnt lgkmcnt(0)
	v_mfma_f32_16x16x32_bf16 v[62:65], v[130:133], v[188:191], v[62:65]
	v_mfma_f32_16x16x32_bf16 v[62:65], v[134:137], v[192:195], v[62:65]
	v_mfma_f32_16x16x32_bf16 v[58:61], v[156:159], v[192:195], v[58:61]
	v_mfma_f32_16x16x32_bf16 v[58:61], v[152:155], v[188:191], v[58:61]
	v_mfma_f32_16x16x32_bf16 v[42:45], v[152:155], v[196:199], v[42:45]
	v_mfma_f32_16x16x32_bf16 v[42:45], v[156:159], v[200:203], v[42:45]
	v_mfma_f32_16x16x32_bf16 v[46:49], v[134:137], v[200:203], v[46:49]
	v_mfma_f32_16x16x32_bf16 v[46:49], v[130:133], v[196:199], v[46:49]
	v_mfma_f32_16x16x32_bf16 v[30:33], v[130:133], v[204:207], v[30:33]
	v_mfma_f32_16x16x32_bf16 v[30:33], v[134:137], v[208:211], v[30:33]
	v_mfma_f32_16x16x32_bf16 v[26:29], v[156:159], v[208:211], v[26:29]
	v_mfma_f32_16x16x32_bf16 v[26:29], v[152:155], v[204:207], v[26:29]
	v_mfma_f32_16x16x32_bf16 v[10:13], v[152:155], v[212:215], v[10:13]
	v_mfma_f32_16x16x32_bf16 v[10:13], v[156:159], v[216:219], v[10:13]
	v_mfma_f32_16x16x32_bf16 v[14:17], v[134:137], v[216:219], v[14:17]
	v_mfma_f32_16x16x32_bf16 v[14:17], v[130:133], v[212:215], v[14:17]
	s_setprio 0
	s_setprio 1
	v_mfma_f32_16x16x32_bf16 v[6:9], v[166:169], v[212:215], v[6:9]
	v_mfma_f32_16x16x32_bf16 v[6:9], v[170:173], v[216:219], v[6:9]
	v_mfma_f32_16x16x32_bf16 v[2:5], v[182:185], v[216:219], v[2:5]
	v_mfma_f32_16x16x32_bf16 v[2:5], v[174:177], v[212:215], v[2:5]
	v_mfma_f32_16x16x32_bf16 v[18:21], v[174:177], v[204:207], v[18:21]
	v_mfma_f32_16x16x32_bf16 v[18:21], v[182:185], v[208:211], v[18:21]
	v_mfma_f32_16x16x32_bf16 v[22:25], v[170:173], v[208:211], v[22:25]
	v_mfma_f32_16x16x32_bf16 v[22:25], v[166:169], v[204:207], v[22:25]
	v_mfma_f32_16x16x32_bf16 v[38:41], v[166:169], v[196:199], v[38:41]
	v_mfma_f32_16x16x32_bf16 v[38:41], v[170:173], v[200:203], v[38:41]
	v_mfma_f32_16x16x32_bf16 v[34:37], v[182:185], v[200:203], v[34:37]
	v_mfma_f32_16x16x32_bf16 v[34:37], v[174:177], v[196:199], v[34:37]
	v_mfma_f32_16x16x32_bf16 v[50:53], v[174:177], v[188:191], v[50:53]
	v_mfma_f32_16x16x32_bf16 v[50:53], v[182:185], v[192:195], v[50:53]
	v_mfma_f32_16x16x32_bf16 v[54:57], v[170:173], v[192:195], v[54:57]
	v_mfma_f32_16x16x32_bf16 v[54:57], v[166:169], v[188:191], v[54:57]
	s_setprio 0
	s_barrier
; #define PG8_STAGE(bufoff, gbase, voff) do { _Pragma("unroll") for (int _i = 0; _i < 2; ++_i) \
;         __builtin_amdgcn_global_load_lds((const unsigned*)((const char*)(gbase) + (voff)[_i]), (PG8_LAS unsigned*)(lds + (bufoff) + ldsw + _i * 8192), 16, 0, 0); } while (0)
; #define PG8_LDA(dst, b, h) do { _Pragma("unroll") for (int m = 0; m < 4; ++m) _Pragma("unroll") for (int k = 0; k < 2; ++k) dst[m][k] = *(const PG8_LAS bf16x8*)(lds + PG8_SA(b, h) + aoff + m * 2048 + k * 1024); } while (0)
; #define PG8_LDB(dst, b, h) do { _Pragma("unroll") for (int n = 0; n < 2; ++n) _Pragma("unroll") for (int k = 0; k < 2; ++k) dst[n][k] = *(const PG8_LAS bf16x8*)(lds + PG8_SB(b, h) + boff + n * 2048 + k * 1024); } while (0)
; #define PG8_MMA(ai, bj, At, Bt) do { __builtin_amdgcn_s_setprio(1); _Pragma("unroll") for (int m = 0; m < 4; ++m) _Pragma("unroll") for (int n = 0; n < 2; ++n) _Pragma("unroll") for (int k = 0; k < 2; ++k) \
;         acc[ai][bj][m][n] = __builtin_amdgcn_mfma_f32_16x16x32_bf16(Bt[n][k], At[m][k], acc[ai][bj][m][n], 0, 0, 0); __builtin_amdgcn_s_setprio(0); } while (0)
; #define PG8_WAIT_V(n) asm volatile("s_waitcnt vmcnt(" #n ")" ::: "memory")
; #define PG8_WAIT_L(n) asm volatile("s_waitcnt lgkmcnt(" #n ")" ::: "memory")
; #define PG8_BAR __builtin_amdgcn_s_barrier()
; #define PG8_SCHED __builtin_amdgcn_sched_barrier(0)
; template <class Epi, class Sched, bool ALIGN_EPI = false, bool SP2 = false, bool RS = false, bool BPRE = false>
; __device__ __forceinline__ void gemm_phase(PG8_LAS unsigned char* lds, const Gemm g, const Sched& S, const Epi& E, const float* rs_ss = nullptr, PG8_LAS float* rs_tab = nullptr) {
;     ...
;             PG8_LDB(B0, 1, 0); PG8_LDB(B1, 1, 1); PG8_SCHED; PG8_LDA(At, 1, 0); PG8_STAGE(PG8_SA(0, 1), a2 + hstep, voffA);
;             PG8_WAIT_V(8); PG8_WAIT_L(0); PG8_BAR; PG8_MMA(0, 0, At, B0); PG8_MMA(0, 1, At, B1); PG8_BAR; PG8_SCHED;
	s_add_i32 s90, 0, 0x18000
	v_add_u32_e32 v143, s90, v160
	s_add_i32 s91, 0, 0x1c000
	ds_read_b128 v[130:133], v143
	ds_read_b128 v[134:137], v143 offset:1024
	ds_read_b128 v[152:155], v143 offset:2048
	ds_read_b128 v[156:159], v143 offset:3072
	s_add_u32 s70, s70, 0x80000
	s_addc_u32 s71, s71, 0
	s_mov_b32 m0, s74
	v_lshl_add_u64 v[178:179], s[70:71], 0, v[138:139]
	global_load_lds_dwordx4 v[178:179], off
	v_add_u32_e32 v143, s91, v160
	ds_read_b128 v[166:169], v143
	ds_read_b128 v[170:173], v143 offset:1024
	ds_read_b128 v[174:177], v143 offset:2048
	ds_read_b128 v[182:185], v143 offset:3072
	v_lshl_add_u64 v[178:179], s[70:71], 0, v[140:141]
	s_mov_b32 m0, s75
	s_nop 0
	global_load_lds_dwordx4 v[178:179], off
	ds_read_b128 v[188:191], v163 offset:32768
	ds_read_b128 v[192:195], v163 offset:33792
	ds_read_b128 v[196:199], v163 offset:34816
	ds_read_b128 v[200:203], v163 offset:35840
	ds_read_b128 v[204:207], v163 offset:36864
	ds_read_b128 v[208:211], v163 offset:37888
	ds_read_b128 v[212:215], v163 offset:38912
	ds_read_b128 v[216:219], v163 offset:39936
	s_waitcnt vmcnt(8)
	s_waitcnt lgkmcnt(0)
	s_barrier
	s_setprio 1
	s_waitcnt lgkmcnt(0)
	v_mfma_f32_16x16x32_bf16 v[126:129], v[130:133], v[188:191], v[126:129]
	v_mfma_f32_16x16x32_bf16 v[126:129], v[134:137], v[192:195], v[126:129]
	v_mfma_f32_16x16x32_bf16 v[122:125], v[156:159], v[192:195], v[122:125]
	v_mfma_f32_16x16x32_bf16 v[122:125], v[152:155], v[188:191], v[122:125]
	v_mfma_f32_16x16x32_bf16 v[106:109], v[152:155], v[196:199], v[106:109]
	v_mfma_f32_16x16x32_bf16 v[106:109], v[156:159], v[200:203], v[106:109]
	v_mfma_f32_16x16x32_bf16 v[110:113], v[134:137], v[200:203], v[110:113]
	v_mfma_f32_16x16x32_bf16 v[110:113], v[130:133], v[196:199], v[110:113]
	v_mfma_f32_16x16x32_bf16 v[94:97], v[130:133], v[204:207], v[94:97]
	v_mfma_f32_16x16x32_bf16 v[94:97], v[134:137], v[208:211], v[94:97]
	v_mfma_f32_16x16x32_bf16 v[90:93], v[156:159], v[208:211], v[90:93]
	v_mfma_f32_16x16x32_bf16 v[90:93], v[152:155], v[204:207], v[90:93]
	v_mfma_f32_16x16x32_bf16 v[74:77], v[152:155], v[212:215], v[74:77]
	v_mfma_f32_16x16x32_bf16 v[74:77], v[156:159], v[216:219], v[74:77]
	v_mfma_f32_16x16x32_bf16 v[78:81], v[134:137], v[216:219], v[78:81]
	v_mfma_f32_16x16x32_bf16 v[78:81], v[130:133], v[212:215], v[78:81]
	s_setprio 0
	s_setprio 1
	v_mfma_f32_16x16x32_bf16 v[70:73], v[166:169], v[212:215], v[70:73]
	v_mfma_f32_16x16x32_bf16 v[70:73], v[170:173], v[216:219], v[70:73]
	v_mfma_f32_16x16x32_bf16 v[66:69], v[182:185], v[216:219], v[66:69]
	v_mfma_f32_16x16x32_bf16 v[66:69], v[174:177], v[212:215], v[66:69]
	v_mfma_f32_16x16x32_bf16 v[82:85], v[174:177], v[204:207], v[82:85]
	v_mfma_f32_16x16x32_bf16 v[82:85], v[182:185], v[208:211], v[82:85]
	v_mfma_f32_16x16x32_bf16 v[86:89], v[170:173], v[208:211], v[86:89]
	v_mfma_f32_16x16x32_bf16 v[86:89], v[166:169], v[204:207], v[86:89]
	v_mfma_f32_16x16x32_bf16 v[102:105], v[166:169], v[196:199], v[102:105]
	v_mfma_f32_16x16x32_bf16 v[102:105], v[170:173], v[200:203], v[102:105]
	v_mfma_f32_16x16x32_bf16 v[98:101], v[182:185], v[200:203], v[98:101]
	v_mfma_f32_16x16x32_bf16 v[98:101], v[174:177], v[196:199], v[98:101]
	v_mfma_f32_16x16x32_bf16 v[114:117], v[174:177], v[188:191], v[114:117]
	v_mfma_f32_16x16x32_bf16 v[114:117], v[182:185], v[192:195], v[114:117]
	v_mfma_f32_16x16x32_bf16 v[118:121], v[170:173], v[192:195], v[118:121]
	v_mfma_f32_16x16x32_bf16 v[118:121], v[166:169], v[188:191], v[118:121]
	s_setprio 0
	s_barrier
; #define PG8_STAGE(bufoff, gbase, voff) do { _Pragma("unroll") for (int _i = 0; _i < 2; ++_i) \
;         __builtin_amdgcn_global_load_lds((const unsigned*)((const char*)(gbase) + (voff)[_i]), (PG8_LAS unsigned*)(lds + (bufoff) + ldsw + _i * 8192), 16, 0, 0); } while (0)
; #define PG8_LDA(dst, b, h) do { _Pragma("unroll") for (int m = 0; m < 4; ++m) _Pragma("unroll") for (int k = 0; k < 2; ++k) dst[m][k] = *(const PG8_LAS bf16x8*)(lds + PG8_SA(b, h) + aoff + m * 2048 + k * 1024); } while (0)
; #define PG8_MMA(ai, bj, At, Bt) do { __builtin_amdgcn_s_setprio(1); _Pragma("unroll") for (int m = 0; m < 4; ++m) _Pragma("unroll") for (int n = 0; n < 2; ++n) _Pragma("unroll") for (int k = 0; k < 2; ++k) \
;         acc[ai][bj][m][n] = __builtin_amdgcn_mfma_f32_16x16x32_bf16(Bt[n][k], At[m][k], acc[ai][bj][m][n], 0, 0, 0); __builtin_amdgcn_s_setprio(0); } while (0)
; #define PG8_WAIT_V(n) asm volatile("s_waitcnt vmcnt(" #n ")" ::: "memory")
; #define PG8_WAIT_L(n) asm volatile("s_waitcnt lgkmcnt(" #n ")" ::: "memory")
; #define PG8_BAR __builtin_amdgcn_s_barrier()
; #define PG8_SCHED __builtin_amdgcn_sched_barrier(0)
; template <class Epi, class Sched, bool ALIGN_EPI = false, bool SP2 = false, bool RS = false, bool BPRE = false>
; __device__ __forceinline__ void gemm_phase(PG8_LAS unsigned char* lds, const Gemm g, const Sched& S, const Epi& E, const float* rs_ss = nullptr, PG8_LAS float* rs_tab = nullptr) {
;     ...
;             PG8_LDA(At, 1, 1); PG8_STAGE(PG8_SB(1, 0), b3, voffB); PG8_STAGE(PG8_SB(1, 1), b3 + hstep, voffB); PG8_STAGE(PG8_SA(1, 0), a3, voffA);
;             PG8_WAIT_V(8); PG8_WAIT_L(0); PG8_BAR; PG8_MMA(1, 0, At, B0); PG8_MMA(1, 1, At, B1); PG8_BAR; PG8_SCHED;
;     ...
;         if constexpr (ALIGN_EPI) { if (wr == 0) PG8_BAR; }
	ds_read_b128 v[188:191], v163 offset:49152
	ds_read_b128 v[192:195], v163 offset:50176
	ds_read_b128 v[196:199], v163 offset:51200
	ds_read_b128 v[200:203], v163 offset:52224
	s_add_u32 s70, s60, 0x4000
	s_addc_u32 s71, s61, 0
	s_add_i32 s90, s90, s15
	v_lshl_add_u64 v[178:179], s[70:71], 0, v[138:139]
	s_mov_b32 m0, s90
	s_nop 0
	global_load_lds_dwordx4 v[178:179], off
	ds_read_b128 v[204:207], v163 offset:53248
	ds_read_b128 v[208:211], v163 offset:54272
	ds_read_b128 v[212:215], v163 offset:55296
	ds_read_b128 v[216:219], v163 offset:56320
	s_add_i32 m0, s90, 0x2000
	s_add_u32 s60, s60, 0x84000
	v_lshl_add_u64 v[178:179], s[70:71], 0, v[140:141]
	s_addc_u32 s61, s61, 0
	s_add_i32 s70, s91, s15
	global_load_lds_dwordx4 v[178:179], off
	v_lshl_add_u64 v[178:179], s[60:61], 0, v[138:139]
	s_mov_b32 m0, s70
	s_nop 0
	global_load_lds_dwordx4 v[178:179], off
	v_lshl_add_u64 v[178:179], s[60:61], 0, v[140:141]
	s_add_i32 m0, s70, 0x2000
	s_nop 0
	global_load_lds_dwordx4 v[178:179], off
	v_lshl_add_u64 v[178:179], s[58:59], 0, v[138:139]
	s_mov_b32 m0, s79
	s_nop 0
	global_load_lds_dwordx4 v[178:179], off
	v_lshl_add_u64 v[178:179], s[58:59], 0, v[140:141]
	s_mov_b32 m0, s80
	s_nop 0
	global_load_lds_dwordx4 v[178:179], off
	s_waitcnt vmcnt(8)
	s_waitcnt lgkmcnt(0)
	s_barrier
	s_setprio 1
	s_waitcnt lgkmcnt(0)
	v_mfma_f32_16x16x32_bf16 v[62:65], v[130:133], v[188:191], v[62:65]
	v_mfma_f32_16x16x32_bf16 v[62:65], v[134:137], v[192:195], v[62:65]
	v_mfma_f32_16x16x32_bf16 v[58:61], v[156:159], v[192:195], v[58:61]
	v_mfma_f32_16x16x32_bf16 v[58:61], v[152:155], v[188:191], v[58:61]
	v_mfma_f32_16x16x32_bf16 v[42:45], v[152:155], v[196:199], v[42:45]
	v_mfma_f32_16x16x32_bf16 v[42:45], v[156:159], v[200:203], v[42:45]
	v_mfma_f32_16x16x32_bf16 v[46:49], v[134:137], v[200:203], v[46:49]
	v_mfma_f32_16x16x32_bf16 v[46:49], v[130:133], v[196:199], v[46:49]
	v_mfma_f32_16x16x32_bf16 v[30:33], v[130:133], v[204:207], v[30:33]
	v_mfma_f32_16x16x32_bf16 v[30:33], v[134:137], v[208:211], v[30:33]
	v_mfma_f32_16x16x32_bf16 v[26:29], v[156:159], v[208:211], v[26:29]
	v_mfma_f32_16x16x32_bf16 v[26:29], v[152:155], v[204:207], v[26:29]
	v_mfma_f32_16x16x32_bf16 v[10:13], v[152:155], v[212:215], v[10:13]
	v_mfma_f32_16x16x32_bf16 v[10:13], v[156:159], v[216:219], v[10:13]
	v_mfma_f32_16x16x32_bf16 v[14:17], v[134:137], v[216:219], v[14:17]
	v_mfma_f32_16x16x32_bf16 v[14:17], v[130:133], v[212:215], v[14:17]
	s_setprio 0
	s_setprio 1
	v_mfma_f32_16x16x32_bf16 v[6:9], v[166:169], v[212:215], v[6:9]
	v_mfma_f32_16x16x32_bf16 v[6:9], v[170:173], v[216:219], v[6:9]
	v_mfma_f32_16x16x32_bf16 v[2:5], v[182:185], v[216:219], v[2:5]
	v_mfma_f32_16x16x32_bf16 v[2:5], v[174:177], v[212:215], v[2:5]
	v_mfma_f32_16x16x32_bf16 v[18:21], v[174:177], v[204:207], v[18:21]
	v_mfma_f32_16x16x32_bf16 v[18:21], v[182:185], v[208:211], v[18:21]
	v_mfma_f32_16x16x32_bf16 v[22:25], v[170:173], v[208:211], v[22:25]
	v_mfma_f32_16x16x32_bf16 v[22:25], v[166:169], v[204:207], v[22:25]
	v_mfma_f32_16x16x32_bf16 v[38:41], v[166:169], v[196:199], v[38:41]
	v_mfma_f32_16x16x32_bf16 v[38:41], v[170:173], v[200:203], v[38:41]
	v_mfma_f32_16x16x32_bf16 v[34:37], v[182:185], v[200:203], v[34:37]
	v_mfma_f32_16x16x32_bf16 v[34:37], v[174:177], v[196:199], v[34:37]
	v_mfma_f32_16x16x32_bf16 v[50:53], v[174:177], v[188:191], v[50:53]
	v_mfma_f32_16x16x32_bf16 v[50:53], v[182:185], v[192:195], v[50:53]
	v_mfma_f32_16x16x32_bf16 v[54:57], v[170:173], v[192:195], v[54:57]
	v_mfma_f32_16x16x32_bf16 v[54:57], v[166:169], v[188:191], v[54:57]
	s_setprio 0
	s_barrier
	s_add_i32 s89, s89, 2
	s_add_u32 s56, s56, 0x8000
	s_addc_u32 s57, s57, 0
	s_add_u32 s87, s87, 0x8000
	s_addc_u32 s88, s88, 0
	s_cmp_gt_u32 s89, 29
	s_cbranch_scc0 .LBB0_196
	s_and_b64 vcc, exec, s[12:13]
	s_cbranch_vccz .LBB0_199
	s_barrier
